# MLP1 and QKV epilogue output stores flagged nt (streamed once-read outputs)
# baseline (speedup 1.0000x reference)
; #define PG8_LAS __attribute__((address_space(3)))
; __device__ __forceinline__ unsigned cvt_pk_bf16(float lo, float hi) { unsigned r; asm volatile("v_cvt_pk_bf16_f32 %0, %1, %2" : "=v"(r) : "v"(lo), "v"(hi)); return r; }
; __device__ __forceinline__ void rstd_from_lds(PG8_LAS unsigned char* lds, int wr, int fr, float (&rs)[2][4]) {
; #pragma unroll
;     for (int ai = 0; ai < 2; ++ai)
; #pragma unroll
;         for (int m = 0; m < 4; ++m) rs[ai][m] = ((const PG8_LAS float*)(lds + RSTD_OFF))[ai * HALF + wr * 64 + m * 16 + fr];
; }
;     __device__ __forceinline__ void operator()(AccT& acc, const Unit& u, int wr, int wc, int fr, int fq, PG8_LAS unsigned char* lds) const {
;         const int rowbase = u.pm * BM + wr * 64 + fr, col0 = u.pn * BM + wc * 32 + 8 * fq;
;         float rs[2][4]; rstd_from_lds(lds, wr, fr, rs);
; #pragma unroll
;         for (int ai = 0; ai < 2; ++ai)
; #pragma unroll
;             for (int m = 0; m < 4; ++m) { bf16_t* rowp = out + (size_t)(rowbase + ai * HALF + m * 16) * 4096 + col0; const float r = rs[ai][m];
; #pragma unroll
;                 for (int bj = 0; bj < 2; ++bj) { f32x4 v0 = acc[ai][bj][m][0] * r, v1 = acc[ai][bj][m][1] * r;
; #pragma unroll
;                     for (int j = 0; j < 4; ++j) { v0[j] = fmaxf(v0[j], 0.f); v0[j] *= v0[j]; v1[j] = fmaxf(v1[j], 0.f); v1[j] *= v1[j]; }
;                     u32x4 w; w.x = cvt_pk_bf16(v0[0], v0[1]); w.y = cvt_pk_bf16(v0[2], v0[3]); w.z = cvt_pk_bf16(v1[0], v1[1]); w.w = cvt_pk_bf16(v1[2], v1[3]);
;                     *(u32x4*)(rowp + bj * HALF) = w; } }
.LBB0_509:
	ds_read2_b32 v[158:159], v153 offset1:16
	ds_read2_b32 v[160:161], v153 offset0:32 offset1:48
	ds_read2_b32 v[146:147], v153 offset0:128 offset1:144
	ds_read2_b32 v[144:145], v153 offset0:160 offset1:176
	v_lshl_add_u32 v156, s10, 8, v148
	s_waitcnt lgkmcnt(0)
	v_pk_mul_f32 v[120:121], v[120:121], v[158:159] op_sel_hi:[1,0]
	v_lshl_or_b32 v142, s46, 8, v151
	v_ashrrev_i32_e32 v157, 31, v156
	v_pk_mul_f32 v[124:125], v[124:125], v[158:159] op_sel_hi:[1,0]
	v_pk_mul_f32 v[122:123], v[122:123], v[158:159] op_sel_hi:[1,0]
	v_max_f32_e32 v120, 0, v120
	v_ashrrev_i32_e32 v143, 31, v142
	v_lshlrev_b64 v[162:163], 13, v[156:157]
	v_pk_mul_f32 v[126:127], v[126:127], v[158:159] op_sel_hi:[1,0]
	v_mul_f32_e32 v155, v120, v120
	v_max_f32_e32 v120, 0, v125
	v_max_f32_e32 v121, 0, v121
	v_max_f32_e32 v122, 0, v122
	v_lshl_add_u64 v[162:163], s[2:3], 0, v[162:163]
	v_lshlrev_b64 v[164:165], 1, v[142:143]
	v_max_f32_e32 v124, 0, v124
	v_mul_f32_e32 v120, v120, v120
	v_mul_f32_e32 v125, v121, v121
	v_max_f32_e32 v121, 0, v126
	v_mul_f32_e32 v126, v122, v122
	v_max_f32_e32 v122, 0, v127
	v_max_f32_e32 v123, 0, v123
	v_pk_mul_f32 v[114:115], v[114:115], v[158:159] op_sel_hi:[1,0]
	v_pk_mul_f32 v[112:113], v[112:113], v[158:159] op_sel_hi:[1,0]
	v_lshl_add_u64 v[142:143], v[162:163], 0, v[164:165]
	v_mul_f32_e32 v124, v124, v124
	v_mul_f32_e32 v121, v121, v121
	v_mul_f32_e32 v122, v122, v122
	v_mul_f32_e32 v123, v123, v123
	v_cvt_pk_bf16_f32 v120, v124, v120
	v_pk_mul_f32 v[118:119], v[118:119], v[158:159] op_sel_hi:[1,0]
	v_pk_mul_f32 v[116:117], v[116:117], v[158:159] op_sel_hi:[1,0]
	v_max_f32_e32 v112, 0, v112
	v_max_f32_e32 v113, 0, v113
	v_max_f32_e32 v114, 0, v114
	v_cvt_pk_bf16_f32 v121, v121, v122
	v_cvt_pk_bf16_f32 v122, v155, v125
	v_cvt_pk_bf16_f32 v123, v126, v123
	global_store_dwordx4 v[142:143], v[120:123], off nt
	v_max_f32_e32 v116, 0, v116
	v_max_f32_e32 v115, 0, v115
	v_mul_f32_e32 v120, v112, v112
	v_max_f32_e32 v112, 0, v117
	v_mul_f32_e32 v117, v113, v113
	v_max_f32_e32 v113, 0, v118
	v_mul_f32_e32 v118, v114, v114
	v_max_f32_e32 v114, 0, v119
	v_mul_f32_e32 v112, v112, v112
	v_mul_f32_e32 v113, v113, v113
	v_mul_f32_e32 v114, v114, v114
	v_mul_f32_e32 v116, v116, v116
	v_mul_f32_e32 v115, v115, v115
	v_cvt_pk_bf16_f32 v112, v116, v112
	v_cvt_pk_bf16_f32 v113, v113, v114
	v_cvt_pk_bf16_f32 v114, v120, v117
	v_cvt_pk_bf16_f32 v115, v118, v115
	global_store_dwordx4 v[142:143], v[112:115], off offset:256 nt
	v_pk_mul_f32 v[88:89], v[88:89], v[160:161] op_sel_hi:[1,0]
	v_pk_mul_f32 v[92:93], v[92:93], v[160:161] op_sel_hi:[1,0]
	v_mov_b32_e32 v114, v159
	v_or_b32_e32 v112, 16, v156
	v_pk_mul_f32 v[104:105], v[104:105], v[114:115] op_sel_hi:[1,0]
	v_ashrrev_i32_e32 v113, 31, v112
	v_pk_mul_f32 v[108:109], v[108:109], v[114:115] op_sel_hi:[1,0]
	v_pk_mul_f32 v[106:107], v[106:107], v[114:115] op_sel_hi:[1,0]
	v_max_f32_e32 v104, 0, v104
	v_lshlrev_b64 v[112:113], 13, v[112:113]
	v_pk_mul_f32 v[110:111], v[110:111], v[114:115] op_sel_hi:[1,0]
	v_mul_f32_e32 v115, v104, v104
	v_max_f32_e32 v104, 0, v109
	v_max_f32_e32 v105, 0, v105
	v_max_f32_e32 v106, 0, v106
	v_lshl_add_u64 v[112:113], s[2:3], 0, v[112:113]
	v_max_f32_e32 v108, 0, v108
	v_mul_f32_e32 v104, v104, v104
	v_mul_f32_e32 v109, v105, v105
	v_max_f32_e32 v105, 0, v110
	v_mul_f32_e32 v110, v106, v106
	v_max_f32_e32 v106, 0, v111
	v_max_f32_e32 v107, 0, v107
	v_pk_mul_f32 v[96:97], v[96:97], v[114:115] op_sel_hi:[1,0]
	v_lshl_add_u64 v[112:113], v[112:113], 0, v[164:165]
	v_mul_f32_e32 v108, v108, v108
	v_mul_f32_e32 v105, v105, v105
	v_mul_f32_e32 v106, v106, v106
	v_mul_f32_e32 v107, v107, v107
	v_cvt_pk_bf16_f32 v104, v108, v104
	v_pk_mul_f32 v[100:101], v[100:101], v[114:115] op_sel_hi:[1,0]
	v_pk_mul_f32 v[98:99], v[98:99], v[114:115] op_sel_hi:[1,0]
	v_max_f32_e32 v96, 0, v96
	v_cvt_pk_bf16_f32 v105, v105, v106
	v_cvt_pk_bf16_f32 v106, v115, v109
	v_cvt_pk_bf16_f32 v107, v110, v107
	global_store_dwordx4 v[112:113], v[104:107], off nt
	v_pk_mul_f32 v[102:103], v[102:103], v[114:115] op_sel_hi:[1,0]
	v_max_f32_e32 v97, 0, v97
	v_mul_f32_e32 v104, v96, v96
	v_max_f32_e32 v96, 0, v101
	v_max_f32_e32 v98, 0, v98
	v_max_f32_e32 v100, 0, v100
	v_mul_f32_e32 v96, v96, v96
	v_mul_f32_e32 v101, v97, v97
	v_max_f32_e32 v97, 0, v102
	v_mul_f32_e32 v102, v98, v98
	v_max_f32_e32 v98, 0, v103
	v_max_f32_e32 v99, 0, v99
	v_mul_f32_e32 v100, v100, v100
	v_mul_f32_e32 v97, v97, v97
	v_mul_f32_e32 v98, v98, v98
	v_mul_f32_e32 v99, v99, v99
	v_cvt_pk_bf16_f32 v96, v100, v96
	v_cvt_pk_bf16_f32 v97, v97, v98
	v_cvt_pk_bf16_f32 v98, v104, v101
	v_cvt_pk_bf16_f32 v99, v102, v99
	global_store_dwordx4 v[112:113], v[96:99], off offset:256 nt
	v_pk_mul_f32 v[90:91], v[90:91], v[160:161] op_sel_hi:[1,0]
	v_max_f32_e32 v88, 0, v88
	v_or_b32_e32 v96, 32, v156
	v_ashrrev_i32_e32 v97, 31, v96
	v_lshlrev_b64 v[96:97], 13, v[96:97]
	v_pk_mul_f32 v[94:95], v[94:95], v[160:161] op_sel_hi:[1,0]
	v_mul_f32_e32 v98, v88, v88
	v_max_f32_e32 v88, 0, v93
	v_max_f32_e32 v89, 0, v89
	v_max_f32_e32 v90, 0, v90
	v_lshl_add_u64 v[96:97], s[2:3], 0, v[96:97]
	v_max_f32_e32 v92, 0, v92
	v_mul_f32_e32 v88, v88, v88
	v_mul_f32_e32 v93, v89, v89
	v_max_f32_e32 v89, 0, v94
	v_mul_f32_e32 v94, v90, v90
	v_max_f32_e32 v90, 0, v95
	v_max_f32_e32 v91, 0, v91
	v_pk_mul_f32 v[82:83], v[82:83], v[160:161] op_sel_hi:[1,0]
	v_pk_mul_f32 v[80:81], v[80:81], v[160:161] op_sel_hi:[1,0]
	v_lshl_add_u64 v[96:97], v[96:97], 0, v[164:165]
	v_mul_f32_e32 v92, v92, v92
	v_mul_f32_e32 v89, v89, v89
	v_mul_f32_e32 v90, v90, v90
	v_mul_f32_e32 v91, v91, v91
	v_cvt_pk_bf16_f32 v88, v92, v88
	v_pk_mul_f32 v[86:87], v[86:87], v[160:161] op_sel_hi:[1,0]
; __device__ __forceinline__ unsigned cvt_pk_bf16(float lo, float hi) { unsigned r; asm volatile("v_cvt_pk_bf16_f32 %0, %1, %2" : "=v"(r) : "v"(lo), "v"(hi)); return r; }
;     __device__ __forceinline__ void operator()(AccT& acc, const Unit& u, int wr, int wc, int fr, int fq, PG8_LAS unsigned char* lds) const {
;     ...
;             for (int m = 0; m < 4; ++m) { bf16_t* rowp = out + (size_t)(rowbase + ai * HALF + m * 16) * 4096 + col0; const float r = rs[ai][m];
; #pragma unroll
;                 for (int bj = 0; bj < 2; ++bj) { f32x4 v0 = acc[ai][bj][m][0] * r, v1 = acc[ai][bj][m][1] * r;
; #pragma unroll
;                     for (int j = 0; j < 4; ++j) { v0[j] = fmaxf(v0[j], 0.f); v0[j] *= v0[j]; v1[j] = fmaxf(v1[j], 0.f); v1[j] *= v1[j]; }
;                     u32x4 w; w.x = cvt_pk_bf16(v0[0], v0[1]); w.y = cvt_pk_bf16(v0[2], v0[3]); w.z = cvt_pk_bf16(v1[0], v1[1]); w.w = cvt_pk_bf16(v1[2], v1[3]);
;                     *(u32x4*)(rowp + bj * HALF) = w; } }
	v_pk_mul_f32 v[84:85], v[84:85], v[160:161] op_sel_hi:[1,0]
	v_max_f32_e32 v80, 0, v80
	v_max_f32_e32 v81, 0, v81
	v_max_f32_e32 v82, 0, v82
	v_cvt_pk_bf16_f32 v89, v89, v90
	v_cvt_pk_bf16_f32 v90, v98, v93
	v_cvt_pk_bf16_f32 v91, v94, v91
	global_store_dwordx4 v[96:97], v[88:91], off nt
	v_max_f32_e32 v84, 0, v84
	v_max_f32_e32 v83, 0, v83
	v_mul_f32_e32 v88, v80, v80
	v_max_f32_e32 v80, 0, v85
	v_mul_f32_e32 v85, v81, v81
	v_max_f32_e32 v81, 0, v86
	v_mul_f32_e32 v86, v82, v82
	v_max_f32_e32 v82, 0, v87
	v_mul_f32_e32 v80, v80, v80
	v_mul_f32_e32 v81, v81, v81
	v_mul_f32_e32 v82, v82, v82
	v_mul_f32_e32 v84, v84, v84
	v_mul_f32_e32 v83, v83, v83
	v_cvt_pk_bf16_f32 v80, v84, v80
	v_cvt_pk_bf16_f32 v81, v81, v82
	v_cvt_pk_bf16_f32 v82, v88, v85
	v_cvt_pk_bf16_f32 v83, v86, v83
	global_store_dwordx4 v[96:97], v[80:83], off offset:256 nt
	v_pk_mul_f32 v[56:57], v[56:57], v[146:147] op_sel_hi:[1,0]
	v_pk_mul_f32 v[60:61], v[60:61], v[146:147] op_sel_hi:[1,0]
	v_mov_b32_e32 v82, v161
	v_or_b32_e32 v80, 48, v156
	v_pk_mul_f32 v[72:73], v[72:73], v[82:83] op_sel_hi:[1,0]
	v_ashrrev_i32_e32 v81, 31, v80
	v_pk_mul_f32 v[76:77], v[76:77], v[82:83] op_sel_hi:[1,0]
	v_pk_mul_f32 v[74:75], v[74:75], v[82:83] op_sel_hi:[1,0]
	v_max_f32_e32 v72, 0, v72
	v_lshlrev_b64 v[80:81], 13, v[80:81]
	v_pk_mul_f32 v[78:79], v[78:79], v[82:83] op_sel_hi:[1,0]
	v_mul_f32_e32 v83, v72, v72
	v_max_f32_e32 v72, 0, v77
	v_max_f32_e32 v73, 0, v73
	v_max_f32_e32 v74, 0, v74
	v_lshl_add_u64 v[80:81], s[2:3], 0, v[80:81]
	v_max_f32_e32 v76, 0, v76
	v_mul_f32_e32 v72, v72, v72
	v_mul_f32_e32 v77, v73, v73
	v_max_f32_e32 v73, 0, v78
	v_mul_f32_e32 v78, v74, v74
	v_max_f32_e32 v74, 0, v79
	v_max_f32_e32 v75, 0, v75
	v_pk_mul_f32 v[66:67], v[66:67], v[82:83] op_sel_hi:[1,0]
	v_pk_mul_f32 v[64:65], v[64:65], v[82:83] op_sel_hi:[1,0]
	v_lshl_add_u64 v[80:81], v[80:81], 0, v[164:165]
	v_mul_f32_e32 v76, v76, v76
	v_mul_f32_e32 v73, v73, v73
	v_mul_f32_e32 v74, v74, v74
	v_mul_f32_e32 v75, v75, v75
	v_cvt_pk_bf16_f32 v72, v76, v72
	v_pk_mul_f32 v[70:71], v[70:71], v[82:83] op_sel_hi:[1,0]
	v_pk_mul_f32 v[68:69], v[68:69], v[82:83] op_sel_hi:[1,0]
	v_max_f32_e32 v64, 0, v64
	v_max_f32_e32 v65, 0, v65
	v_max_f32_e32 v66, 0, v66
	v_cvt_pk_bf16_f32 v73, v73, v74
	v_cvt_pk_bf16_f32 v74, v83, v77
	v_cvt_pk_bf16_f32 v75, v78, v75
	global_store_dwordx4 v[80:81], v[72:75], off nt
	v_max_f32_e32 v68, 0, v68
	v_max_f32_e32 v67, 0, v67
	v_mul_f32_e32 v72, v64, v64
	v_max_f32_e32 v64, 0, v69
	v_mul_f32_e32 v69, v65, v65
	v_max_f32_e32 v65, 0, v70
	v_mul_f32_e32 v70, v66, v66
	v_max_f32_e32 v66, 0, v71
	v_mul_f32_e32 v64, v64, v64
	v_mul_f32_e32 v65, v65, v65
	v_mul_f32_e32 v66, v66, v66
	v_mul_f32_e32 v68, v68, v68
	v_mul_f32_e32 v67, v67, v67
	v_cvt_pk_bf16_f32 v64, v68, v64
	v_cvt_pk_bf16_f32 v65, v65, v66
	v_cvt_pk_bf16_f32 v66, v72, v69
	v_pk_mul_f32 v[58:59], v[58:59], v[146:147] op_sel_hi:[1,0]
	v_max_f32_e32 v56, 0, v56
	v_cvt_pk_bf16_f32 v67, v70, v67
	global_store_dwordx4 v[80:81], v[64:67], off offset:256 nt
	s_mov_b64 s[10:11], 0x100000
	v_pk_mul_f32 v[62:63], v[62:63], v[146:147] op_sel_hi:[1,0]
	v_max_f32_e32 v60, 0, v60
	v_mul_f32_e32 v66, v56, v56
	v_max_f32_e32 v56, 0, v61
	v_max_f32_e32 v57, 0, v57
	v_max_f32_e32 v58, 0, v58
	v_lshl_add_u64 v[64:65], v[142:143], 0, s[10:11]
	v_mul_f32_e32 v60, v60, v60
	v_mul_f32_e32 v56, v56, v56
	v_mul_f32_e32 v61, v57, v57
	v_max_f32_e32 v57, 0, v62
	v_mul_f32_e32 v62, v58, v58
	v_max_f32_e32 v58, 0, v63
	s_mov_b32 s10, 0x100000
	v_mul_f32_e32 v57, v57, v57
	v_mul_f32_e32 v58, v58, v58
	v_max_f32_e32 v59, 0, v59
	v_cvt_pk_bf16_f32 v56, v60, v56
	v_add_co_u32_e32 v60, vcc, s10, v142
	v_pk_mul_f32 v[50:51], v[50:51], v[146:147] op_sel_hi:[1,0]
	v_pk_mul_f32 v[48:49], v[48:49], v[146:147] op_sel_hi:[1,0]
	v_mul_f32_e32 v59, v59, v59
	v_cvt_pk_bf16_f32 v57, v57, v58
	v_cvt_pk_bf16_f32 v58, v66, v61
	v_addc_co_u32_e32 v61, vcc, 0, v143, vcc
	v_pk_mul_f32 v[54:55], v[54:55], v[146:147] op_sel_hi:[1,0]
	v_pk_mul_f32 v[52:53], v[52:53], v[146:147] op_sel_hi:[1,0]
	v_max_f32_e32 v48, 0, v48
	v_max_f32_e32 v49, 0, v49
	v_max_f32_e32 v50, 0, v50
	v_cvt_pk_bf16_f32 v59, v62, v59
	global_store_dwordx4 v[60:61], v[56:59], off nt
	v_max_f32_e32 v52, 0, v52
	v_max_f32_e32 v51, 0, v51
	v_mul_f32_e32 v56, v48, v48
	v_max_f32_e32 v48, 0, v53
	v_mul_f32_e32 v53, v49, v49
	v_max_f32_e32 v49, 0, v54
	v_mul_f32_e32 v54, v50, v50
	v_max_f32_e32 v50, 0, v55
	v_mul_f32_e32 v48, v48, v48
	v_mul_f32_e32 v49, v49, v49
	v_mul_f32_e32 v50, v50, v50
	v_mul_f32_e32 v52, v52, v52
	v_mul_f32_e32 v51, v51, v51
	v_cvt_pk_bf16_f32 v48, v52, v48
	v_cvt_pk_bf16_f32 v49, v49, v50
	v_cvt_pk_bf16_f32 v50, v56, v53
	v_cvt_pk_bf16_f32 v51, v54, v51
	global_store_dwordx4 v[64:65], v[48:51], off offset:256 nt
	s_mov_b64 s[10:11], 0x120000
	v_pk_mul_f32 v[24:25], v[24:25], v[144:145] op_sel_hi:[1,0]
	v_mov_b32_e32 v50, v147
	v_pk_mul_f32 v[40:41], v[40:41], v[50:51] op_sel_hi:[1,0]
	v_pk_mul_f32 v[44:45], v[44:45], v[50:51] op_sel_hi:[1,0]
	v_pk_mul_f32 v[42:43], v[42:43], v[50:51] op_sel_hi:[1,0]
	v_max_f32_e32 v40, 0, v40
	v_pk_mul_f32 v[46:47], v[46:47], v[50:51] op_sel_hi:[1,0]
	v_max_f32_e32 v44, 0, v44
	v_mul_f32_e32 v51, v40, v40
	v_max_f32_e32 v40, 0, v45
	v_max_f32_e32 v41, 0, v41
	v_max_f32_e32 v42, 0, v42
	v_lshl_add_u64 v[48:49], v[142:143], 0, s[10:11]
; __device__ __forceinline__ unsigned cvt_pk_bf16(float lo, float hi) { unsigned r; asm volatile("v_cvt_pk_bf16_f32 %0, %1, %2" : "=v"(r) : "v"(lo), "v"(hi)); return r; }
;     __device__ __forceinline__ void operator()(AccT& acc, const Unit& u, int wr, int wc, int fr, int fq, PG8_LAS unsigned char* lds) const {
;     ...
;             for (int m = 0; m < 4; ++m) { bf16_t* rowp = out + (size_t)(rowbase + ai * HALF + m * 16) * 4096 + col0; const float r = rs[ai][m];
; #pragma unroll
;                 for (int bj = 0; bj < 2; ++bj) { f32x4 v0 = acc[ai][bj][m][0] * r, v1 = acc[ai][bj][m][1] * r;
; #pragma unroll
;                     for (int j = 0; j < 4; ++j) { v0[j] = fmaxf(v0[j], 0.f); v0[j] *= v0[j]; v1[j] = fmaxf(v1[j], 0.f); v1[j] *= v1[j]; }
;                     u32x4 w; w.x = cvt_pk_bf16(v0[0], v0[1]); w.y = cvt_pk_bf16(v0[2], v0[3]); w.z = cvt_pk_bf16(v1[0], v1[1]); w.w = cvt_pk_bf16(v1[2], v1[3]);
;                     *(u32x4*)(rowp + bj * HALF) = w; } }
	v_mul_f32_e32 v44, v44, v44
	v_mul_f32_e32 v40, v40, v40
	v_mul_f32_e32 v45, v41, v41
	v_max_f32_e32 v41, 0, v46
	v_mul_f32_e32 v46, v42, v42
	v_max_f32_e32 v42, 0, v47
	s_mov_b32 s10, 0x120000
	v_mul_f32_e32 v41, v41, v41
	v_mul_f32_e32 v42, v42, v42
	v_max_f32_e32 v43, 0, v43
	v_cvt_pk_bf16_f32 v40, v44, v40
	v_add_co_u32_e32 v44, vcc, s10, v142
	v_pk_mul_f32 v[34:35], v[34:35], v[50:51] op_sel_hi:[1,0]
	v_pk_mul_f32 v[32:33], v[32:33], v[50:51] op_sel_hi:[1,0]
	v_mul_f32_e32 v43, v43, v43
	v_cvt_pk_bf16_f32 v41, v41, v42
	v_cvt_pk_bf16_f32 v42, v51, v45
	v_addc_co_u32_e32 v45, vcc, 0, v143, vcc
	v_pk_mul_f32 v[38:39], v[38:39], v[50:51] op_sel_hi:[1,0]
	v_pk_mul_f32 v[36:37], v[36:37], v[50:51] op_sel_hi:[1,0]
	v_max_f32_e32 v32, 0, v32
	v_max_f32_e32 v33, 0, v33
	v_max_f32_e32 v34, 0, v34
	v_cvt_pk_bf16_f32 v43, v46, v43
	global_store_dwordx4 v[44:45], v[40:43], off nt
	v_max_f32_e32 v36, 0, v36
	v_max_f32_e32 v35, 0, v35
	v_mul_f32_e32 v40, v32, v32
	v_max_f32_e32 v32, 0, v37
	v_mul_f32_e32 v37, v33, v33
	v_max_f32_e32 v33, 0, v38
	v_mul_f32_e32 v38, v34, v34
	v_max_f32_e32 v34, 0, v39
	v_mul_f32_e32 v32, v32, v32
	v_mul_f32_e32 v33, v33, v33
	v_mul_f32_e32 v34, v34, v34
	v_mul_f32_e32 v36, v36, v36
	v_mul_f32_e32 v35, v35, v35
	v_cvt_pk_bf16_f32 v32, v36, v32
	v_cvt_pk_bf16_f32 v33, v33, v34
	v_cvt_pk_bf16_f32 v34, v40, v37
	v_pk_mul_f32 v[28:29], v[28:29], v[144:145] op_sel_hi:[1,0]
	v_pk_mul_f32 v[26:27], v[26:27], v[144:145] op_sel_hi:[1,0]
	v_max_f32_e32 v24, 0, v24
	v_cvt_pk_bf16_f32 v35, v38, v35
	global_store_dwordx4 v[48:49], v[32:35], off offset:256 nt
	s_mov_b64 s[10:11], 0x140000
	v_pk_mul_f32 v[30:31], v[30:31], v[144:145] op_sel_hi:[1,0]
	v_max_f32_e32 v28, 0, v28
	v_mul_f32_e32 v34, v24, v24
	v_max_f32_e32 v24, 0, v29
	v_max_f32_e32 v25, 0, v25
	v_max_f32_e32 v26, 0, v26
	v_lshl_add_u64 v[32:33], v[142:143], 0, s[10:11]
	v_mul_f32_e32 v28, v28, v28
	v_mul_f32_e32 v24, v24, v24
	v_mul_f32_e32 v29, v25, v25
	v_max_f32_e32 v25, 0, v30
	v_mul_f32_e32 v30, v26, v26
	v_max_f32_e32 v26, 0, v31
	s_mov_b32 s10, 0x140000
	v_mul_f32_e32 v25, v25, v25
	v_mul_f32_e32 v26, v26, v26
	v_max_f32_e32 v27, 0, v27
	v_cvt_pk_bf16_f32 v24, v28, v24
	v_add_co_u32_e32 v28, vcc, s10, v142
	v_pk_mul_f32 v[18:19], v[18:19], v[144:145] op_sel_hi:[1,0]
	v_pk_mul_f32 v[16:17], v[16:17], v[144:145] op_sel_hi:[1,0]
	v_mul_f32_e32 v27, v27, v27
	v_cvt_pk_bf16_f32 v25, v25, v26
	v_cvt_pk_bf16_f32 v26, v34, v29
	v_addc_co_u32_e32 v29, vcc, 0, v143, vcc
	v_pk_mul_f32 v[22:23], v[22:23], v[144:145] op_sel_hi:[1,0]
	v_pk_mul_f32 v[20:21], v[20:21], v[144:145] op_sel_hi:[1,0]
	v_max_f32_e32 v16, 0, v16
	v_max_f32_e32 v17, 0, v17
	v_max_f32_e32 v18, 0, v18
	v_cvt_pk_bf16_f32 v27, v30, v27
	global_store_dwordx4 v[28:29], v[24:27], off nt
	v_max_f32_e32 v20, 0, v20
	v_max_f32_e32 v19, 0, v19
	v_mul_f32_e32 v24, v16, v16
	v_max_f32_e32 v16, 0, v21
	v_mul_f32_e32 v21, v17, v17
	v_max_f32_e32 v17, 0, v22
	v_mul_f32_e32 v22, v18, v18
	v_max_f32_e32 v18, 0, v23
	v_mul_f32_e32 v16, v16, v16
	v_mul_f32_e32 v17, v17, v17
	v_mul_f32_e32 v18, v18, v18
	v_mul_f32_e32 v20, v20, v20
	v_mul_f32_e32 v19, v19, v19
	v_cvt_pk_bf16_f32 v16, v20, v16
	v_cvt_pk_bf16_f32 v17, v17, v18
	v_cvt_pk_bf16_f32 v18, v24, v21
	v_cvt_pk_bf16_f32 v19, v22, v19
	global_store_dwordx4 v[32:33], v[16:19], off offset:256 nt
	s_mov_b64 s[10:11], 0x160000
	s_nop 0
	v_mov_b32_e32 v18, v145
	v_pk_mul_f32 v[8:9], v[8:9], v[18:19] op_sel_hi:[1,0]
	v_pk_mul_f32 v[12:13], v[12:13], v[18:19] op_sel_hi:[1,0]
	v_pk_mul_f32 v[10:11], v[10:11], v[18:19] op_sel_hi:[1,0]
	v_max_f32_e32 v8, 0, v8
	v_pk_mul_f32 v[14:15], v[14:15], v[18:19] op_sel_hi:[1,0]
	v_max_f32_e32 v12, 0, v12
	v_mul_f32_e32 v19, v8, v8
	v_max_f32_e32 v8, 0, v13
	v_max_f32_e32 v9, 0, v9
	v_max_f32_e32 v10, 0, v10
	v_lshl_add_u64 v[16:17], v[142:143], 0, s[10:11]
	v_mul_f32_e32 v12, v12, v12
	v_mul_f32_e32 v8, v8, v8
	v_mul_f32_e32 v13, v9, v9
	v_max_f32_e32 v9, 0, v14
	v_mul_f32_e32 v14, v10, v10
	v_max_f32_e32 v10, 0, v15
	s_mov_b32 s10, 0x160000
	v_mul_f32_e32 v9, v9, v9
	v_mul_f32_e32 v10, v10, v10
	v_max_f32_e32 v11, 0, v11
	v_cvt_pk_bf16_f32 v8, v12, v8
	v_add_co_u32_e32 v12, vcc, s10, v142
	v_pk_mul_f32 v[2:3], v[2:3], v[18:19] op_sel_hi:[1,0]
	v_pk_mul_f32 v[0:1], v[0:1], v[18:19] op_sel_hi:[1,0]
	v_mul_f32_e32 v11, v11, v11
	v_cvt_pk_bf16_f32 v9, v9, v10
	v_cvt_pk_bf16_f32 v10, v19, v13
	v_addc_co_u32_e32 v13, vcc, 0, v143, vcc
	v_pk_mul_f32 v[6:7], v[6:7], v[18:19] op_sel_hi:[1,0]
	v_pk_mul_f32 v[4:5], v[4:5], v[18:19] op_sel_hi:[1,0]
	v_max_f32_e32 v0, 0, v0
	v_max_f32_e32 v1, 0, v1
	v_max_f32_e32 v2, 0, v2
	v_cvt_pk_bf16_f32 v11, v14, v11
	global_store_dwordx4 v[12:13], v[8:11], off nt
	v_max_f32_e32 v3, 0, v3
	v_max_f32_e32 v4, 0, v4
	v_mul_f32_e32 v8, v0, v0
	v_max_f32_e32 v0, 0, v5
	v_mul_f32_e32 v5, v1, v1
	v_max_f32_e32 v1, 0, v6
	v_mul_f32_e32 v6, v2, v2
	v_max_f32_e32 v2, 0, v7
	v_mul_f32_e32 v0, v0, v0
	v_mul_f32_e32 v1, v1, v1
	v_mul_f32_e32 v2, v2, v2
	v_mul_f32_e32 v3, v3, v3
	s_andn2_b64 vcc, exec, s[38:39]
	s_mov_b64 s[10:11], -1
	v_mul_f32_e32 v4, v4, v4
	v_cvt_pk_bf16_f32 v0, v4, v0
	v_cvt_pk_bf16_f32 v1, v1, v2
	v_cvt_pk_bf16_f32 v2, v8, v5
	v_cvt_pk_bf16_f32 v3, v6, v3
	global_store_dwordx4 v[16:17], v[0:3], off offset:256 nt
	s_cbranch_vccnz .LBB0_513
	s_andn2_b64 vcc, exec, s[0:1]
	s_cbranch_vccnz .LBB0_512
	s_barrier

; __device__ __forceinline__ unsigned cvt_pk_bf16(float lo, float hi) { unsigned r; asm volatile("v_cvt_pk_bf16_f32 %0, %1, %2" : "=v"(r) : "v"(lo), "v"(hi)); return r; }
;     __device__ __forceinline__ void operator()(AccT& acc, const Unit& u, int wr, int wc, int fr, int fq, PG8_LAS unsigned char* lds) const {
;     ...
; #pragma unroll
;         for (int ai = 0; ai < 2; ++ai)
; #pragma unroll
;             for (int m = 0; m < 4; ++m) { bf16_t* rowp = out + (size_t)(rowbase + ai * HALF + m * 16) * ldc + col0;
; #pragma unroll
;                 for (int bj = 0; bj < 2; ++bj) { const float r = normed ? rn[ai][m][NSEG == 1 ? 0 : bj] : rs[ai][m];
;                     const f32x4 v0 = acc[ai][bj][m][0] * gv[bj][0] * r, v1 = acc[ai][bj][m][1] * gv[bj][1] * r;
;                     u32x4 w; w.x = cvt_pk_bf16(v0[0], v0[1]); w.y = cvt_pk_bf16(v0[2], v0[3]); w.z = cvt_pk_bf16(v1[0], v1[1]); w.w = cvt_pk_bf16(v1[2], v1[3]);
;                     *(u32x4*)(rowp + bj * HALF) = w; } }
.LBB0_767:
	v_lshl_or_b32 v182, s61, 8, v189
	v_lshl_add_u32 v196, s18, 8, v184
	v_ashrrev_i32_e32 v183, 31, v182
	v_mov_b64_e32 v[180:181], s[10:11]
	s_movk_i32 s2, 0x1800
	v_mad_i64_i32 v[192:193], s[0:1], v196, s2, v[180:181]
	v_lshlrev_b64 v[182:183], 1, v[182:183]
	s_waitcnt vmcnt(0)
	v_pk_mul_f32 v[126:127], v[126:127], v[134:135]
	v_pk_mul_f32 v[124:125], v[124:125], v[132:133]
	v_pk_mul_f32 v[122:123], v[122:123], v[130:131]
	v_pk_mul_f32 v[120:121], v[120:121], v[128:129]
	v_lshl_add_u64 v[192:193], v[192:193], 0, v[182:183]
	v_pk_mul_f32 v[126:127], v[126:127], v[164:165] op_sel_hi:[1,0]
	v_pk_mul_f32 v[124:125], v[124:125], v[164:165] op_sel_hi:[1,0]
	v_pk_mul_f32 v[194:195], v[122:123], v[164:165] op_sel_hi:[1,0]
	v_pk_mul_f32 v[122:123], v[120:121], v[164:165] op_sel_hi:[1,0]
	v_cvt_pk_bf16_f32 v120, v124, v125
	v_cvt_pk_bf16_f32 v121, v126, v127
	v_pk_mul_f32 v[116:117], v[116:117], v[140:141]
	v_pk_mul_f32 v[110:111], v[110:111], v[138:139]
	v_pk_mul_f32 v[108:109], v[108:109], v[136:137]
	v_cvt_pk_bf16_f32 v122, v122, v123
	v_cvt_pk_bf16_f32 v123, v194, v195
	global_store_dwordx4 v[192:193], v[120:123], off nt
	v_pk_mul_f32 v[118:119], v[118:119], v[142:143]
	v_pk_mul_f32 v[116:117], v[116:117], v[162:163] op_sel_hi:[1,0]
	v_pk_mul_f32 v[120:121], v[110:111], v[162:163] op_sel_hi:[1,0]
	v_pk_mul_f32 v[110:111], v[108:109], v[162:163] op_sel_hi:[1,0]
	v_cvt_pk_bf16_f32 v108, v116, v117
	v_pk_mul_f32 v[118:119], v[118:119], v[162:163] op_sel_hi:[1,0]
	v_pk_mul_f32 v[112:113], v[112:113], v[132:133]
	v_cvt_pk_bf16_f32 v109, v118, v119
	v_cvt_pk_bf16_f32 v110, v110, v111
	v_cvt_pk_bf16_f32 v111, v120, v121
	global_store_dwordx4 v[192:193], v[108:111], off offset:256 nt
	v_pk_mul_f32 v[106:107], v[106:107], v[130:131]
	v_pk_mul_f32 v[104:105], v[104:105], v[128:129]
	v_or_b32_e32 v108, 16, v196
	v_mad_i64_i32 v[108:109], s[0:1], v108, s2, v[180:181]
	v_lshl_add_u64 v[108:109], v[108:109], 0, v[182:183]
	v_pk_mul_f32 v[110:111], v[114:115], v[134:135]
	v_pk_mul_f32 v[112:113], v[112:113], v[166:167] op_sel_hi:[1,0]
	v_pk_mul_f32 v[114:115], v[106:107], v[166:167] op_sel_hi:[1,0]
	v_pk_mul_f32 v[106:107], v[104:105], v[166:167] op_sel_hi:[1,0]
	v_cvt_pk_bf16_f32 v104, v112, v113
	v_pk_mul_f32 v[110:111], v[110:111], v[166:167] op_sel_hi:[1,0]
	v_pk_mul_f32 v[100:101], v[100:101], v[140:141]
	v_cvt_pk_bf16_f32 v105, v110, v111
	v_cvt_pk_bf16_f32 v106, v106, v107
	v_cvt_pk_bf16_f32 v107, v114, v115
	global_store_dwordx4 v[108:109], v[104:107], off nt
	v_pk_mul_f32 v[94:95], v[94:95], v[138:139]
	v_pk_mul_f32 v[92:93], v[92:93], v[136:137]
	v_mov_b32_e32 v104, v163
	v_pk_mul_f32 v[102:103], v[102:103], v[142:143]
	v_pk_mul_f32 v[100:101], v[100:101], v[104:105] op_sel_hi:[1,0]
	v_pk_mul_f32 v[106:107], v[94:95], v[104:105] op_sel_hi:[1,0]
	v_pk_mul_f32 v[94:95], v[92:93], v[104:105] op_sel_hi:[1,0]
	v_cvt_pk_bf16_f32 v92, v100, v101
	v_pk_mul_f32 v[102:103], v[102:103], v[104:105] op_sel_hi:[1,0]
	v_pk_mul_f32 v[96:97], v[96:97], v[132:133]
	v_cvt_pk_bf16_f32 v93, v102, v103
	v_cvt_pk_bf16_f32 v94, v94, v95
	v_cvt_pk_bf16_f32 v95, v106, v107
	global_store_dwordx4 v[108:109], v[92:95], off offset:256 nt
	v_pk_mul_f32 v[90:91], v[90:91], v[130:131]
	v_pk_mul_f32 v[88:89], v[88:89], v[128:129]
	v_or_b32_e32 v92, 32, v196
	v_mad_i64_i32 v[92:93], s[0:1], v92, s2, v[180:181]
	v_pk_mul_f32 v[94:95], v[98:99], v[134:135]
	v_lshl_add_u64 v[92:93], v[92:93], 0, v[182:183]
	v_pk_mul_f32 v[94:95], v[94:95], v[168:169] op_sel_hi:[1,0]
	v_pk_mul_f32 v[96:97], v[96:97], v[168:169] op_sel_hi:[1,0]
	v_pk_mul_f32 v[98:99], v[90:91], v[168:169] op_sel_hi:[1,0]
	v_pk_mul_f32 v[90:91], v[88:89], v[168:169] op_sel_hi:[1,0]
	v_cvt_pk_bf16_f32 v88, v96, v97
	v_cvt_pk_bf16_f32 v89, v94, v95
	v_pk_mul_f32 v[84:85], v[84:85], v[140:141]
	v_pk_mul_f32 v[78:79], v[78:79], v[138:139]
	v_pk_mul_f32 v[76:77], v[76:77], v[136:137]
	v_cvt_pk_bf16_f32 v90, v90, v91
	v_cvt_pk_bf16_f32 v91, v98, v99
	global_store_dwordx4 v[92:93], v[88:91], off nt
	v_pk_mul_f32 v[86:87], v[86:87], v[142:143]
	v_pk_mul_f32 v[84:85], v[84:85], v[160:161] op_sel_hi:[1,0]
	v_pk_mul_f32 v[88:89], v[78:79], v[160:161] op_sel_hi:[1,0]
	v_pk_mul_f32 v[78:79], v[76:77], v[160:161] op_sel_hi:[1,0]
	v_cvt_pk_bf16_f32 v76, v84, v85
	v_pk_mul_f32 v[86:87], v[86:87], v[160:161] op_sel_hi:[1,0]
	v_pk_mul_f32 v[80:81], v[80:81], v[132:133]
	v_cvt_pk_bf16_f32 v77, v86, v87
	v_cvt_pk_bf16_f32 v78, v78, v79
	v_cvt_pk_bf16_f32 v79, v88, v89
	global_store_dwordx4 v[92:93], v[76:79], off offset:256 nt
	v_pk_mul_f32 v[74:75], v[74:75], v[130:131]
	v_pk_mul_f32 v[72:73], v[72:73], v[128:129]
	v_or_b32_e32 v76, 48, v196
	v_mad_i64_i32 v[76:77], s[0:1], v76, s2, v[180:181]
	v_lshl_add_u64 v[76:77], v[76:77], 0, v[182:183]
	v_pk_mul_f32 v[78:79], v[82:83], v[134:135]
	v_pk_mul_f32 v[80:81], v[80:81], v[170:171] op_sel_hi:[1,0]
	v_pk_mul_f32 v[82:83], v[74:75], v[170:171] op_sel_hi:[1,0]
	v_pk_mul_f32 v[74:75], v[72:73], v[170:171] op_sel_hi:[1,0]
	v_cvt_pk_bf16_f32 v72, v80, v81
	v_pk_mul_f32 v[78:79], v[78:79], v[170:171] op_sel_hi:[1,0]
	v_pk_mul_f32 v[68:69], v[68:69], v[140:141]
	v_cvt_pk_bf16_f32 v73, v78, v79
	v_cvt_pk_bf16_f32 v74, v74, v75
	v_cvt_pk_bf16_f32 v75, v82, v83
	global_store_dwordx4 v[76:77], v[72:75], off nt
	v_pk_mul_f32 v[66:67], v[66:67], v[138:139]
	v_pk_mul_f32 v[64:65], v[64:65], v[136:137]
	v_mov_b32_e32 v72, v161
	v_pk_mul_f32 v[70:71], v[70:71], v[142:143]
	v_pk_mul_f32 v[68:69], v[68:69], v[72:73] op_sel_hi:[1,0]
	v_pk_mul_f32 v[74:75], v[66:67], v[72:73] op_sel_hi:[1,0]
	v_pk_mul_f32 v[66:67], v[64:65], v[72:73] op_sel_hi:[1,0]
	v_cvt_pk_bf16_f32 v64, v68, v69
; __device__ __forceinline__ unsigned cvt_pk_bf16(float lo, float hi) { unsigned r; asm volatile("v_cvt_pk_bf16_f32 %0, %1, %2" : "=v"(r) : "v"(lo), "v"(hi)); return r; }
;     __device__ __forceinline__ void operator()(AccT& acc, const Unit& u, int wr, int wc, int fr, int fq, PG8_LAS unsigned char* lds) const {
;     ...
; #pragma unroll
;         for (int ai = 0; ai < 2; ++ai)
; #pragma unroll
;             for (int m = 0; m < 4; ++m) { bf16_t* rowp = out + (size_t)(rowbase + ai * HALF + m * 16) * ldc + col0;
; #pragma unroll
;                 for (int bj = 0; bj < 2; ++bj) { const float r = normed ? rn[ai][m][NSEG == 1 ? 0 : bj] : rs[ai][m];
;                     const f32x4 v0 = acc[ai][bj][m][0] * gv[bj][0] * r, v1 = acc[ai][bj][m][1] * gv[bj][1] * r;
;                     u32x4 w; w.x = cvt_pk_bf16(v0[0], v0[1]); w.y = cvt_pk_bf16(v0[2], v0[3]); w.z = cvt_pk_bf16(v1[0], v1[1]); w.w = cvt_pk_bf16(v1[2], v1[3]);
;                     *(u32x4*)(rowp + bj * HALF) = w; } }
	v_pk_mul_f32 v[70:71], v[70:71], v[72:73] op_sel_hi:[1,0]
	v_pk_mul_f32 v[62:63], v[62:63], v[134:135]
	v_cvt_pk_bf16_f32 v65, v70, v71
	v_cvt_pk_bf16_f32 v66, v66, v67
	v_cvt_pk_bf16_f32 v67, v74, v75
	global_store_dwordx4 v[76:77], v[64:67], off offset:256 nt
	v_pk_mul_f32 v[60:61], v[60:61], v[132:133]
	v_pk_mul_f32 v[58:59], v[58:59], v[130:131]
	v_add_u32_e32 v64, 0x80, v196
	v_mad_i64_i32 v[64:65], s[0:1], v64, s2, v[180:181]
	v_pk_mul_f32 v[56:57], v[56:57], v[128:129]
	v_lshl_add_u64 v[64:65], v[64:65], 0, v[182:183]
	v_pk_mul_f32 v[62:63], v[62:63], v[172:173] op_sel_hi:[1,0]
	v_pk_mul_f32 v[60:61], v[60:61], v[172:173] op_sel_hi:[1,0]
	v_pk_mul_f32 v[66:67], v[58:59], v[172:173] op_sel_hi:[1,0]
	v_pk_mul_f32 v[58:59], v[56:57], v[172:173] op_sel_hi:[1,0]
	v_cvt_pk_bf16_f32 v56, v60, v61
	v_cvt_pk_bf16_f32 v57, v62, v63
	v_pk_mul_f32 v[52:53], v[52:53], v[140:141]
	v_pk_mul_f32 v[46:47], v[46:47], v[138:139]
	v_pk_mul_f32 v[44:45], v[44:45], v[136:137]
	v_cvt_pk_bf16_f32 v58, v58, v59
	v_cvt_pk_bf16_f32 v59, v66, v67
	global_store_dwordx4 v[64:65], v[56:59], off nt
	v_pk_mul_f32 v[54:55], v[54:55], v[142:143]
	v_pk_mul_f32 v[52:53], v[52:53], v[158:159] op_sel_hi:[1,0]
	v_pk_mul_f32 v[56:57], v[46:47], v[158:159] op_sel_hi:[1,0]
	v_pk_mul_f32 v[46:47], v[44:45], v[158:159] op_sel_hi:[1,0]
	v_cvt_pk_bf16_f32 v44, v52, v53
	v_pk_mul_f32 v[54:55], v[54:55], v[158:159] op_sel_hi:[1,0]
	v_pk_mul_f32 v[48:49], v[48:49], v[132:133]
	v_cvt_pk_bf16_f32 v45, v54, v55
	v_cvt_pk_bf16_f32 v46, v46, v47
	v_cvt_pk_bf16_f32 v47, v56, v57
	global_store_dwordx4 v[64:65], v[44:47], off offset:256 nt
	v_pk_mul_f32 v[42:43], v[42:43], v[130:131]
	v_pk_mul_f32 v[40:41], v[40:41], v[128:129]
	v_add_u32_e32 v44, 0x90, v196
	v_mad_i64_i32 v[44:45], s[0:1], v44, s2, v[180:181]
	v_lshl_add_u64 v[44:45], v[44:45], 0, v[182:183]
	v_pk_mul_f32 v[46:47], v[50:51], v[134:135]
	v_pk_mul_f32 v[48:49], v[48:49], v[174:175] op_sel_hi:[1,0]
	v_pk_mul_f32 v[50:51], v[42:43], v[174:175] op_sel_hi:[1,0]
	v_pk_mul_f32 v[42:43], v[40:41], v[174:175] op_sel_hi:[1,0]
	v_cvt_pk_bf16_f32 v40, v48, v49
	v_pk_mul_f32 v[46:47], v[46:47], v[174:175] op_sel_hi:[1,0]
	v_pk_mul_f32 v[36:37], v[36:37], v[140:141]
	v_cvt_pk_bf16_f32 v41, v46, v47
	v_cvt_pk_bf16_f32 v42, v42, v43
	v_cvt_pk_bf16_f32 v43, v50, v51
	global_store_dwordx4 v[44:45], v[40:43], off nt
	v_pk_mul_f32 v[30:31], v[30:31], v[138:139]
	v_pk_mul_f32 v[28:29], v[28:29], v[136:137]
	v_mov_b32_e32 v40, v159
	v_pk_mul_f32 v[38:39], v[38:39], v[142:143]
	v_pk_mul_f32 v[36:37], v[36:37], v[40:41] op_sel_hi:[1,0]
	v_pk_mul_f32 v[42:43], v[30:31], v[40:41] op_sel_hi:[1,0]
	v_pk_mul_f32 v[30:31], v[28:29], v[40:41] op_sel_hi:[1,0]
	v_cvt_pk_bf16_f32 v28, v36, v37
	v_pk_mul_f32 v[38:39], v[38:39], v[40:41] op_sel_hi:[1,0]
	v_pk_mul_f32 v[32:33], v[32:33], v[132:133]
	v_cvt_pk_bf16_f32 v29, v38, v39
	v_cvt_pk_bf16_f32 v30, v30, v31
	v_cvt_pk_bf16_f32 v31, v42, v43
	global_store_dwordx4 v[44:45], v[28:31], off offset:256 nt
	v_pk_mul_f32 v[26:27], v[26:27], v[130:131]
	v_pk_mul_f32 v[24:25], v[24:25], v[128:129]
	v_add_u32_e32 v28, 0xa0, v196
	v_mad_i64_i32 v[28:29], s[0:1], v28, s2, v[180:181]
	v_pk_mul_f32 v[30:31], v[34:35], v[134:135]
	v_lshl_add_u64 v[28:29], v[28:29], 0, v[182:183]
	v_pk_mul_f32 v[30:31], v[30:31], v[178:179] op_sel_hi:[1,0]
	v_pk_mul_f32 v[32:33], v[32:33], v[178:179] op_sel_hi:[1,0]
	v_pk_mul_f32 v[34:35], v[26:27], v[178:179] op_sel_hi:[1,0]
	v_pk_mul_f32 v[26:27], v[24:25], v[178:179] op_sel_hi:[1,0]
	v_cvt_pk_bf16_f32 v24, v32, v33
	v_cvt_pk_bf16_f32 v25, v30, v31
	v_pk_mul_f32 v[20:21], v[20:21], v[140:141]
	v_pk_mul_f32 v[14:15], v[14:15], v[138:139]
	v_pk_mul_f32 v[12:13], v[12:13], v[136:137]
	v_cvt_pk_bf16_f32 v26, v26, v27
	v_cvt_pk_bf16_f32 v27, v34, v35
	global_store_dwordx4 v[28:29], v[24:27], off nt
	v_pk_mul_f32 v[22:23], v[22:23], v[142:143]
	v_pk_mul_f32 v[20:21], v[20:21], v[156:157] op_sel_hi:[1,0]
	v_pk_mul_f32 v[24:25], v[14:15], v[156:157] op_sel_hi:[1,0]
	v_pk_mul_f32 v[14:15], v[12:13], v[156:157] op_sel_hi:[1,0]
	v_cvt_pk_bf16_f32 v12, v20, v21
	v_pk_mul_f32 v[22:23], v[22:23], v[156:157] op_sel_hi:[1,0]
	v_pk_mul_f32 v[16:17], v[16:17], v[132:133]
	v_cvt_pk_bf16_f32 v13, v22, v23
	v_cvt_pk_bf16_f32 v14, v14, v15
	v_cvt_pk_bf16_f32 v15, v24, v25
	global_store_dwordx4 v[28:29], v[12:15], off offset:256 nt
	v_pk_mul_f32 v[10:11], v[10:11], v[130:131]
	v_pk_mul_f32 v[8:9], v[8:9], v[128:129]
	v_add_u32_e32 v12, 0xb0, v196
	v_mad_i64_i32 v[12:13], s[0:1], v12, s2, v[180:181]
	v_lshl_add_u64 v[12:13], v[12:13], 0, v[182:183]
	v_pk_mul_f32 v[14:15], v[18:19], v[134:135]
	v_pk_mul_f32 v[16:17], v[16:17], v[176:177] op_sel_hi:[1,0]
	v_pk_mul_f32 v[18:19], v[10:11], v[176:177] op_sel_hi:[1,0]
	v_pk_mul_f32 v[10:11], v[8:9], v[176:177] op_sel_hi:[1,0]
	v_cvt_pk_bf16_f32 v8, v16, v17
	v_pk_mul_f32 v[14:15], v[14:15], v[176:177] op_sel_hi:[1,0]
	v_pk_mul_f32 v[2:3], v[2:3], v[138:139]
	v_cvt_pk_bf16_f32 v9, v14, v15
	v_cvt_pk_bf16_f32 v10, v10, v11
	v_cvt_pk_bf16_f32 v11, v18, v19
	global_store_dwordx4 v[12:13], v[8:11], off nt
	v_pk_mul_f32 v[0:1], v[0:1], v[136:137]
	v_pk_mul_f32 v[6:7], v[6:7], v[142:143]
	v_mov_b32_e32 v8, v157
	v_pk_mul_f32 v[4:5], v[4:5], v[140:141]
	v_pk_mul_f32 v[10:11], v[2:3], v[8:9] op_sel_hi:[1,0]
	v_pk_mul_f32 v[2:3], v[0:1], v[8:9] op_sel_hi:[1,0]
	s_andn2_b64 vcc, exec, s[38:39]
	s_mov_b64 s[0:1], -1
	v_pk_mul_f32 v[6:7], v[6:7], v[8:9] op_sel_hi:[1,0]
	v_pk_mul_f32 v[4:5], v[4:5], v[8:9] op_sel_hi:[1,0]
	s_nop 0
	v_cvt_pk_bf16_f32 v0, v4, v5
	v_cvt_pk_bf16_f32 v1, v6, v7
	v_cvt_pk_bf16_f32 v2, v2, v3
	v_cvt_pk_bf16_f32 v3, v10, v11
	global_store_dwordx4 v[12:13], v[0:3], off offset:256 nt
	s_cbranch_vccnz .LBB0_698
	s_andn2_b64 vcc, exec, s[4:5]
	s_cbranch_vccnz .LBB0_697
	s_barrier
	s_branch .LBB0_697
